# MLA q up-projection epilogue: 16 serialized row-norm reloads replaced by two batched loads (same summation order)
# speedup vs baseline: 1.0048x; 1.0048x over previous
;     __device__ __forceinline__ void operator()(const f32x4 (&acc)[2][2][4][2], const Unit& u, int wr, int wc, int fr, int fq) const {
;         { const int t_ = opaque_tid(), w_ = __builtin_amdgcn_readfirstlane(t_ >> 6), l_ = t_ & 63; wr = w_ >> 2; wc = w_ & 3; fr = l_ & 15; fq = l_ >> 4; }
;         const int row0 = u.pm * BM + wr * 64 + fr;
; #pragma unroll
;         for (int bj = 0; bj < 2; ++bj) { const int n = u.pn * BM + bj * HALF + wc * 32 + fq * 8;
;             if (n < NUQ) {
; #pragma unroll
;             for (int ai = 0; ai < 2; ++ai)
; #pragma unroll
;                 for (int m = 0; m < 4; ++m) { const int row = row0 + ai * HALF + m * 16;
;                     const float r = __builtin_amdgcn_rsqf(sum_parts<3>(ssq + (size_t)row * 12) * (1.0f / 384.0f) + 1e-6f) * SC_A; float v[8];
.LBB0_595:
	s_getreg_b32 s22, hwreg(HW_REG_HW_ID, 0, 6)
	s_lshl_b32 s22, s22, 2
	s_and_b32 s22, s22, 0xfc
	s_add_i32 s22, s22, 0x20040
	v_mov_b32_e32 v136, s22
	ds_read_b32 v136, v136
	v_mov_b32_e32 v137, 0
	s_waitcnt lgkmcnt(0)
	v_readfirstlane_b32 s22, v136
	v_mbcnt_lo_u32_b32 v137, -1, v137
	v_mbcnt_hi_u32_b32 v137, -1, v137
	v_lshl_or_b32 v136, s22, 6, v137
	s_nop 0
	v_readfirstlane_b32 s22, v136
	s_ashr_i32 s23, s22, 2
	s_lshr_b32 s22, s22, 1
	s_andn2_b32 s23, s23, 63
	s_and_b32 s22, s22, 0x60
	v_lshrrev_b32_e32 v136, 1, v137
	v_and_or_b32 v136, v136, 24, s22
	v_and_or_b32 v137, v137, 15, s23
	v_lshl_add_u32 v147, s50, 8, v137
	v_lshl_or_b32 v136, s33, 8, v136
	s_movk_i32 s22, 0x480
	v_cmp_gt_i32_e32 vcc, s22, v136
	v_ashrrev_i32_e32 v137, 31, v136
	v_or_b32_e32 v146, 16, v147
	v_or_b32_e32 v145, 32, v147
	v_or_b32_e32 v144, 48, v147
	v_add_u32_e32 v143, 0x80, v147
	v_add_u32_e32 v142, 0x90, v147
	v_add_u32_e32 v141, 0xa0, v147
	v_add_u32_e32 v140, 0xb0, v147
	v_mad_i64_i32 v[218:219], s[24:25], v147, 48, s[6:7]
	global_load_dwordx4 v[168:171], v[218:219], off offset:32
	global_load_dwordx4 v[160:163], v[218:219], off
	global_load_dwordx4 v[164:167], v[218:219], off offset:16
	v_mad_i64_i32 v[220:221], s[24:25], v146, 48, s[6:7]
	global_load_dwordx4 v[180:183], v[220:221], off offset:32
	global_load_dwordx4 v[172:175], v[220:221], off
	global_load_dwordx4 v[176:179], v[220:221], off offset:16
	v_mad_i64_i32 v[222:223], s[24:25], v145, 48, s[6:7]
	global_load_dwordx4 v[192:195], v[222:223], off offset:32
	global_load_dwordx4 v[184:187], v[222:223], off
	global_load_dwordx4 v[188:191], v[222:223], off offset:16
	v_mad_i64_i32 v[224:225], s[24:25], v144, 48, s[6:7]
	global_load_dwordx4 v[238:241], v[224:225], off offset:32
	global_load_dwordx4 v[196:199], v[224:225], off
	global_load_dwordx4 v[234:237], v[224:225], off offset:16
	s_waitcnt vmcnt(0)
	v_pk_add_f32 v[162:163], v[162:163], v[166:167]
	v_pk_add_f32 v[160:161], v[160:161], v[164:165]
	v_pk_add_f32 v[162:163], v[162:163], v[170:171]
	v_pk_add_f32 v[160:161], v[160:161], v[168:169]
	v_add_f32_e32 v160, v161, v160
	v_add_f32_e32 v162, v162, v163
	v_add_f32_e32 v226, v160, v162
	v_fmamk_f32 v226, v226, 0x3b2aaaab, v204
	v_pk_add_f32 v[174:175], v[174:175], v[178:179]
	v_pk_add_f32 v[172:173], v[172:173], v[176:177]
	v_pk_add_f32 v[174:175], v[174:175], v[182:183]
	v_pk_add_f32 v[172:173], v[172:173], v[180:181]
	v_add_f32_e32 v172, v173, v172
	v_add_f32_e32 v174, v174, v175
	v_add_f32_e32 v227, v172, v174
	v_fmamk_f32 v227, v227, 0x3b2aaaab, v204
	v_pk_add_f32 v[186:187], v[186:187], v[190:191]
	v_pk_add_f32 v[184:185], v[184:185], v[188:189]
	v_pk_add_f32 v[186:187], v[186:187], v[194:195]
	v_pk_add_f32 v[184:185], v[184:185], v[192:193]
	v_add_f32_e32 v184, v185, v184
	v_add_f32_e32 v186, v186, v187
	v_add_f32_e32 v228, v184, v186
	v_fmamk_f32 v228, v228, 0x3b2aaaab, v204
	v_pk_add_f32 v[198:199], v[198:199], v[236:237]
	v_pk_add_f32 v[196:197], v[196:197], v[234:235]
	v_pk_add_f32 v[198:199], v[198:199], v[240:241]
	v_pk_add_f32 v[196:197], v[196:197], v[238:239]
	v_add_f32_e32 v196, v197, v196
	v_add_f32_e32 v198, v198, v199
	v_add_f32_e32 v229, v196, v198
	v_fmamk_f32 v229, v229, 0x3b2aaaab, v204
	v_rsq_f32_e32 v226, v226
	v_rsq_f32_e32 v227, v227
	v_rsq_f32_e32 v228, v228
	v_rsq_f32_e32 v229, v229
	s_nop 0
	v_mul_f32_e32 v226, 0x3dd53b94, v226
	v_mul_f32_e32 v227, 0x3dd53b94, v227
	v_mul_f32_e32 v228, 0x3dd53b94, v228
	v_mul_f32_e32 v229, 0x3dd53b94, v229
	v_mad_i64_i32 v[218:219], s[24:25], v143, 48, s[6:7]
	global_load_dwordx4 v[168:171], v[218:219], off offset:32
	global_load_dwordx4 v[160:163], v[218:219], off
	global_load_dwordx4 v[164:167], v[218:219], off offset:16
	v_mad_i64_i32 v[220:221], s[24:25], v142, 48, s[6:7]
	global_load_dwordx4 v[180:183], v[220:221], off offset:32
	global_load_dwordx4 v[172:175], v[220:221], off
	global_load_dwordx4 v[176:179], v[220:221], off offset:16
	v_mad_i64_i32 v[222:223], s[24:25], v141, 48, s[6:7]
	global_load_dwordx4 v[192:195], v[222:223], off offset:32
	global_load_dwordx4 v[184:187], v[222:223], off
	global_load_dwordx4 v[188:191], v[222:223], off offset:16
	v_mad_i64_i32 v[224:225], s[24:25], v140, 48, s[6:7]
	global_load_dwordx4 v[238:241], v[224:225], off offset:32
	global_load_dwordx4 v[196:199], v[224:225], off
	global_load_dwordx4 v[234:237], v[224:225], off offset:16
	s_waitcnt vmcnt(0)
	v_pk_add_f32 v[162:163], v[162:163], v[166:167]
	v_pk_add_f32 v[160:161], v[160:161], v[164:165]
	v_pk_add_f32 v[162:163], v[162:163], v[170:171]
	v_pk_add_f32 v[160:161], v[160:161], v[168:169]
	v_add_f32_e32 v160, v161, v160
	v_add_f32_e32 v162, v162, v163
	v_add_f32_e32 v230, v160, v162
	v_fmamk_f32 v230, v230, 0x3b2aaaab, v204
	v_pk_add_f32 v[174:175], v[174:175], v[178:179]
	v_pk_add_f32 v[172:173], v[172:173], v[176:177]
	v_pk_add_f32 v[174:175], v[174:175], v[182:183]
	v_pk_add_f32 v[172:173], v[172:173], v[180:181]
	v_add_f32_e32 v172, v173, v172
	v_add_f32_e32 v174, v174, v175
	v_add_f32_e32 v231, v172, v174
	v_fmamk_f32 v231, v231, 0x3b2aaaab, v204
	v_pk_add_f32 v[186:187], v[186:187], v[190:191]
	v_pk_add_f32 v[184:185], v[184:185], v[188:189]
	v_pk_add_f32 v[186:187], v[186:187], v[194:195]
	v_pk_add_f32 v[184:185], v[184:185], v[192:193]
	v_add_f32_e32 v184, v185, v184
	v_add_f32_e32 v186, v186, v187
	v_add_f32_e32 v232, v184, v186
	v_fmamk_f32 v232, v232, 0x3b2aaaab, v204
	v_pk_add_f32 v[198:199], v[198:199], v[236:237]
	v_pk_add_f32 v[196:197], v[196:197], v[234:235]
	v_pk_add_f32 v[198:199], v[198:199], v[240:241]
	v_pk_add_f32 v[196:197], v[196:197], v[238:239]
	v_add_f32_e32 v196, v197, v196
	v_add_f32_e32 v198, v198, v199
	v_add_f32_e32 v233, v196, v198
	v_fmamk_f32 v233, v233, 0x3b2aaaab, v204
	v_rsq_f32_e32 v230, v230
	v_rsq_f32_e32 v231, v231
	v_rsq_f32_e32 v232, v232
	v_rsq_f32_e32 v233, v233
	s_nop 0
	v_mul_f32_e32 v230, 0x3dd53b94, v230
	v_mul_f32_e32 v231, 0x3dd53b94, v231
	v_mul_f32_e32 v232, 0x3dd53b94, v232
	v_mul_f32_e32 v233, 0x3dd53b94, v233
	s_and_saveexec_b64 s[22:23], vcc
	s_cbranch_execz .LBB0_597
;     __device__ __forceinline__ void operator()(const f32x4 (&acc)[2][2][4][2], const Unit& u, int wr, int wc, int fr, int fq) const {
;     ...
;         for (int bj = 0; bj < 2; ++bj) { const int n = u.pn * BM + bj * HALF + wc * 32 + fq * 8;
;             if (n < NUQ) {
; #pragma unroll
;             for (int ai = 0; ai < 2; ++ai)
; #pragma unroll
;                 for (int m = 0; m < 4; ++m) { const int row = row0 + ai * HALF + m * 16;
;                     const float r = __builtin_amdgcn_rsqf(sum_parts<3>(ssq + (size_t)row * 12) * (1.0f / 384.0f) + 1e-6f) * SC_A; float v[8];
; #pragma unroll
;                     for (int e = 0; e < 4; ++e) { v[e] = acc[ai][bj][m][0][e] * r; v[4 + e] = acc[ai][bj][m][1][e] * r; }
;                     store8(Q + (size_t)row * NUQ + n, v); asm volatile("" ::: "memory"); } } }
	s_movk_i32 s33, 0x900
	s_nop 1
	v_mov_b32_e32 v148, v226
	v_mul_f32_e32 v150, v122, v148
	v_mul_f32_e32 v152, v123, v148
	v_mov_b64_e32 v[122:123], s[8:9]
	v_mul_f32_e32 v151, v126, v148
	v_mul_f32_e32 v153, v127, v148
	v_mul_f32_e32 v154, v124, v148
	v_mul_f32_e32 v155, v128, v148
	v_mul_f32_e32 v128, v125, v148
	v_mad_i64_i32 v[126:127], s[24:25], v147, s33, v[122:123]
	v_lshlrev_b64 v[124:125], 1, v[136:137]
	v_mul_f32_e32 v129, v129, v148
	v_lshl_add_u64 v[148:149], v[126:127], 0, v[124:125]
	v_cvt_pk_bf16_f32 v126, v150, v152
	v_cvt_pk_bf16_f32 v127, v154, v128
	v_cvt_pk_bf16_f32 v128, v151, v153
	v_cvt_pk_bf16_f32 v129, v155, v129
	global_store_dwordx4 v[148:149], v[126:129], off
	s_nop 1
	v_mov_b32_e32 v126, v227
	v_mul_f32_e32 v127, v114, v126
	v_mul_f32_e32 v129, v115, v126
	v_mad_i64_i32 v[114:115], s[24:25], v146, s33, v[122:123]
	v_mul_f32_e32 v128, v118, v126
	v_mul_f32_e32 v148, v119, v126
	v_mul_f32_e32 v116, v116, v126
	v_mul_f32_e32 v117, v117, v126
	v_lshl_add_u64 v[118:119], v[114:115], 0, v[124:125]
	v_mul_f32_e32 v120, v120, v126
	v_mul_f32_e32 v121, v121, v126
	v_cvt_pk_bf16_f32 v114, v127, v129
	v_cvt_pk_bf16_f32 v115, v116, v117
	v_cvt_pk_bf16_f32 v116, v128, v148
	v_cvt_pk_bf16_f32 v117, v120, v121
	global_store_dwordx4 v[118:119], v[114:117], off
	s_nop 1
	v_mov_b32_e32 v114, v228
	v_mul_f32_e32 v115, v106, v114
	v_mul_f32_e32 v117, v107, v114
	v_mad_i64_i32 v[106:107], s[24:25], v145, s33, v[122:123]
	v_mul_f32_e32 v116, v110, v114
	v_mul_f32_e32 v118, v111, v114
	v_mul_f32_e32 v108, v108, v114
	v_mul_f32_e32 v109, v109, v114
	v_lshl_add_u64 v[110:111], v[106:107], 0, v[124:125]
	v_mul_f32_e32 v112, v112, v114
	v_mul_f32_e32 v113, v113, v114
	v_cvt_pk_bf16_f32 v106, v115, v117
	v_cvt_pk_bf16_f32 v107, v108, v109
	v_cvt_pk_bf16_f32 v108, v116, v118
	v_cvt_pk_bf16_f32 v109, v112, v113
	global_store_dwordx4 v[110:111], v[106:109], off
	s_nop 1
	v_mov_b32_e32 v106, v229
	v_mul_f32_e32 v107, v98, v106
	v_mul_f32_e32 v109, v99, v106
	v_mad_i64_i32 v[98:99], s[24:25], v144, s33, v[122:123]
	v_mul_f32_e32 v108, v102, v106
	v_mul_f32_e32 v110, v103, v106
	v_mul_f32_e32 v100, v100, v106
	v_mul_f32_e32 v101, v101, v106
	v_lshl_add_u64 v[102:103], v[98:99], 0, v[124:125]
	v_mul_f32_e32 v104, v104, v106
	v_mul_f32_e32 v105, v105, v106
	v_cvt_pk_bf16_f32 v98, v107, v109
	v_cvt_pk_bf16_f32 v99, v100, v101
	v_cvt_pk_bf16_f32 v100, v108, v110
	v_cvt_pk_bf16_f32 v101, v104, v105
	global_store_dwordx4 v[102:103], v[98:101], off
	s_nop 1
	v_mov_b32_e32 v98, v230
	v_mul_f32_e32 v99, v90, v98
	v_mul_f32_e32 v101, v91, v98
	v_mad_i64_i32 v[90:91], s[24:25], v143, s33, v[122:123]
	v_mul_f32_e32 v100, v94, v98
	v_mul_f32_e32 v102, v95, v98
	v_mul_f32_e32 v92, v92, v98
	v_mul_f32_e32 v93, v93, v98
	v_lshl_add_u64 v[94:95], v[90:91], 0, v[124:125]
	v_mul_f32_e32 v96, v96, v98
	v_mul_f32_e32 v97, v97, v98
	v_cvt_pk_bf16_f32 v90, v99, v101
	v_cvt_pk_bf16_f32 v91, v92, v93
	v_cvt_pk_bf16_f32 v92, v100, v102
	v_cvt_pk_bf16_f32 v93, v96, v97
	global_store_dwordx4 v[94:95], v[90:93], off
	s_nop 1
	v_mov_b32_e32 v90, v231
	v_mul_f32_e32 v91, v82, v90
	v_mul_f32_e32 v93, v83, v90
	v_mad_i64_i32 v[82:83], s[24:25], v142, s33, v[122:123]
	v_mul_f32_e32 v92, v86, v90
	v_mul_f32_e32 v94, v87, v90
	v_mul_f32_e32 v84, v84, v90
	v_mul_f32_e32 v85, v85, v90
	v_lshl_add_u64 v[86:87], v[82:83], 0, v[124:125]
	v_mul_f32_e32 v88, v88, v90
	v_mul_f32_e32 v89, v89, v90
	v_cvt_pk_bf16_f32 v82, v91, v93
	v_cvt_pk_bf16_f32 v83, v84, v85
	v_cvt_pk_bf16_f32 v84, v92, v94
	v_cvt_pk_bf16_f32 v85, v88, v89
	global_store_dwordx4 v[86:87], v[82:85], off
	s_nop 1
	v_mov_b32_e32 v82, v232
	v_mul_f32_e32 v83, v74, v82
	v_mul_f32_e32 v85, v75, v82
	v_mad_i64_i32 v[74:75], s[24:25], v141, s33, v[122:123]
	v_mul_f32_e32 v84, v78, v82
	v_mul_f32_e32 v86, v79, v82
	v_mul_f32_e32 v76, v76, v82
	v_mul_f32_e32 v77, v77, v82
	v_lshl_add_u64 v[78:79], v[74:75], 0, v[124:125]
	v_mul_f32_e32 v80, v80, v82
	v_mul_f32_e32 v81, v81, v82
	v_cvt_pk_bf16_f32 v74, v83, v85
	v_cvt_pk_bf16_f32 v75, v76, v77
	v_cvt_pk_bf16_f32 v76, v84, v86
	v_cvt_pk_bf16_f32 v77, v80, v81
	global_store_dwordx4 v[78:79], v[74:77], off
	s_nop 1
	v_mov_b32_e32 v74, v233
	v_mul_f32_e32 v75, v66, v74
	v_mul_f32_e32 v77, v67, v74
	v_mad_i64_i32 v[66:67], s[24:25], v140, s33, v[122:123]
	v_mul_f32_e32 v76, v70, v74
	v_mul_f32_e32 v78, v71, v74
	v_mul_f32_e32 v68, v68, v74
	v_mul_f32_e32 v69, v69, v74
	v_lshl_add_u64 v[70:71], v[66:67], 0, v[124:125]
	v_mul_f32_e32 v72, v72, v74
	v_mul_f32_e32 v73, v73, v74
	v_cvt_pk_bf16_f32 v66, v75, v77
	v_cvt_pk_bf16_f32 v67, v68, v69
	v_cvt_pk_bf16_f32 v68, v76, v78
	v_cvt_pk_bf16_f32 v69, v72, v73
	global_store_dwordx4 v[70:71], v[66:69], off
;     __device__ __forceinline__ void operator()(const f32x4 (&acc)[2][2][4][2], const Unit& u, int wr, int wc, int fr, int fq) const {
;     ...
;         for (int bj = 0; bj < 2; ++bj) { const int n = u.pn * BM + bj * HALF + wc * 32 + fq * 8;
;             if (n < NUQ) {
; #pragma unroll
;             for (int ai = 0; ai < 2; ++ai)
; #pragma unroll
;                 for (int m = 0; m < 4; ++m) { const int row = row0 + ai * HALF + m * 16;
;                     const float r = __builtin_amdgcn_rsqf(sum_parts<3>(ssq + (size_t)row * 12) * (1.0f / 384.0f) + 1e-6f) * SC_A; float v[8];
; #pragma unroll
;                     for (int e = 0; e < 4; ++e) { v[e] = acc[ai][bj][m][0][e] * r; v[4 + e] = acc[ai][bj][m][1][e] * r; }
;                     store8(Q + (size_t)row * NUQ + n, v); asm volatile("" ::: "memory"); } } }
.LBB0_597:
	s_or_b64 exec, exec, s[22:23]
	s_nop 0
	v_or_b32_e32 v66, 0x80, v136
	s_movk_i32 s22, 0x480
	v_cmp_gt_i32_e32 vcc, s22, v66
	s_and_saveexec_b64 s[22:23], vcc
	s_cbranch_execz .LBB0_599
	s_movk_i32 s33, 0x900
	s_nop 1
	v_mov_b32_e32 v66, v226
	v_mul_f32_e32 v68, v58, v66
	v_mul_f32_e32 v70, v59, v66
	v_mov_b64_e32 v[58:59], s[8:9]
	v_mul_f32_e32 v69, v62, v66
	v_mul_f32_e32 v71, v63, v66
	v_mul_f32_e32 v72, v60, v66
	v_mul_f32_e32 v73, v64, v66
	v_mul_f32_e32 v64, v61, v66
	v_mad_i64_i32 v[62:63], s[24:25], v147, s33, v[58:59]
	v_lshlrev_b64 v[60:61], 1, v[136:137]
	v_mul_f32_e32 v65, v65, v66
	v_lshl_add_u64 v[66:67], v[62:63], 0, v[60:61]
	v_cvt_pk_bf16_f32 v62, v68, v70
	v_cvt_pk_bf16_f32 v63, v72, v64
	v_cvt_pk_bf16_f32 v64, v69, v71
	v_cvt_pk_bf16_f32 v65, v73, v65
	global_store_dwordx4 v[66:67], v[62:65], off offset:256
	s_nop 1
	v_mov_b32_e32 v62, v227
	v_mul_f32_e32 v63, v50, v62
	v_mul_f32_e32 v65, v51, v62
	v_mad_i64_i32 v[50:51], s[24:25], v146, s33, v[58:59]
	v_mul_f32_e32 v64, v54, v62
	v_mul_f32_e32 v66, v55, v62
	v_mul_f32_e32 v52, v52, v62
	v_mul_f32_e32 v53, v53, v62
	v_lshl_add_u64 v[54:55], v[50:51], 0, v[60:61]
	v_mul_f32_e32 v56, v56, v62
	v_mul_f32_e32 v57, v57, v62
	v_cvt_pk_bf16_f32 v50, v63, v65
	v_cvt_pk_bf16_f32 v51, v52, v53
	v_cvt_pk_bf16_f32 v52, v64, v66
	v_cvt_pk_bf16_f32 v53, v56, v57
	global_store_dwordx4 v[54:55], v[50:53], off offset:256
	s_nop 1
	v_mov_b32_e32 v50, v228
	v_mul_f32_e32 v51, v42, v50
	v_mul_f32_e32 v53, v43, v50
	v_mad_i64_i32 v[42:43], s[24:25], v145, s33, v[58:59]
	v_mul_f32_e32 v52, v46, v50
	v_mul_f32_e32 v54, v47, v50
	v_mul_f32_e32 v44, v44, v50
	v_mul_f32_e32 v45, v45, v50
	v_lshl_add_u64 v[46:47], v[42:43], 0, v[60:61]
	v_mul_f32_e32 v48, v48, v50
	v_mul_f32_e32 v49, v49, v50
	v_cvt_pk_bf16_f32 v42, v51, v53
	v_cvt_pk_bf16_f32 v43, v44, v45
	v_cvt_pk_bf16_f32 v44, v52, v54
	v_cvt_pk_bf16_f32 v45, v48, v49
	global_store_dwordx4 v[46:47], v[42:45], off offset:256
	s_nop 1
	v_mov_b32_e32 v42, v229
	v_mul_f32_e32 v43, v34, v42
	v_mul_f32_e32 v45, v35, v42
	v_mad_i64_i32 v[34:35], s[24:25], v144, s33, v[58:59]
	v_mul_f32_e32 v44, v38, v42
	v_mul_f32_e32 v46, v39, v42
	v_mul_f32_e32 v36, v36, v42
	v_mul_f32_e32 v37, v37, v42
	v_lshl_add_u64 v[38:39], v[34:35], 0, v[60:61]
	v_mul_f32_e32 v40, v40, v42
	v_mul_f32_e32 v41, v41, v42
	v_cvt_pk_bf16_f32 v34, v43, v45
	v_cvt_pk_bf16_f32 v35, v36, v37
	v_cvt_pk_bf16_f32 v36, v44, v46
	v_cvt_pk_bf16_f32 v37, v40, v41
	global_store_dwordx4 v[38:39], v[34:37], off offset:256
	s_nop 1
	v_mov_b32_e32 v34, v230
	v_mul_f32_e32 v35, v26, v34
	v_mul_f32_e32 v37, v27, v34
	v_mad_i64_i32 v[26:27], s[24:25], v143, s33, v[58:59]
	v_mul_f32_e32 v36, v30, v34
	v_mul_f32_e32 v38, v31, v34
	v_mul_f32_e32 v28, v28, v34
	v_mul_f32_e32 v29, v29, v34
	v_lshl_add_u64 v[30:31], v[26:27], 0, v[60:61]
	v_mul_f32_e32 v32, v32, v34
	v_mul_f32_e32 v33, v33, v34
	v_cvt_pk_bf16_f32 v26, v35, v37
	v_cvt_pk_bf16_f32 v27, v28, v29
	v_cvt_pk_bf16_f32 v28, v36, v38
	v_cvt_pk_bf16_f32 v29, v32, v33
	global_store_dwordx4 v[30:31], v[26:29], off offset:256
	s_nop 1
	v_mov_b32_e32 v26, v231
	v_mul_f32_e32 v27, v18, v26
	v_mul_f32_e32 v29, v19, v26
	v_mad_i64_i32 v[18:19], s[24:25], v142, s33, v[58:59]
	v_mul_f32_e32 v28, v22, v26
	v_mul_f32_e32 v30, v23, v26
	v_mul_f32_e32 v20, v20, v26
	v_mul_f32_e32 v21, v21, v26
	v_lshl_add_u64 v[22:23], v[18:19], 0, v[60:61]
	v_mul_f32_e32 v24, v24, v26
	v_mul_f32_e32 v25, v25, v26
	v_cvt_pk_bf16_f32 v18, v27, v29
	v_cvt_pk_bf16_f32 v19, v20, v21
	v_cvt_pk_bf16_f32 v20, v28, v30
	v_cvt_pk_bf16_f32 v21, v24, v25
	global_store_dwordx4 v[22:23], v[18:21], off offset:256
	s_nop 1
	v_mov_b32_e32 v18, v232
	v_mul_f32_e32 v19, v10, v18
	v_mul_f32_e32 v21, v11, v18
	v_mad_i64_i32 v[10:11], s[24:25], v141, s33, v[58:59]
	v_mul_f32_e32 v20, v14, v18
	v_mul_f32_e32 v22, v15, v18
	v_mul_f32_e32 v12, v12, v18
	v_mul_f32_e32 v13, v13, v18
	v_lshl_add_u64 v[14:15], v[10:11], 0, v[60:61]
	v_mul_f32_e32 v16, v16, v18
	v_mul_f32_e32 v17, v17, v18
	v_cvt_pk_bf16_f32 v10, v19, v21
	v_cvt_pk_bf16_f32 v11, v12, v13
	v_cvt_pk_bf16_f32 v12, v20, v22
	v_cvt_pk_bf16_f32 v13, v16, v17
	global_store_dwordx4 v[14:15], v[10:13], off offset:256
	s_nop 1
	v_mov_b32_e32 v10, v233
	v_mul_f32_e32 v11, v2, v10
	v_mul_f32_e32 v13, v3, v10
	v_mad_i64_i32 v[2:3], s[24:25], v140, s33, v[58:59]
	v_mul_f32_e32 v12, v6, v10
	v_mul_f32_e32 v14, v7, v10
	v_mul_f32_e32 v4, v4, v10
	v_mul_f32_e32 v5, v5, v10
	v_lshl_add_u64 v[6:7], v[2:3], 0, v[60:61]
	v_mul_f32_e32 v8, v8, v10
	v_mul_f32_e32 v9, v9, v10
	v_cvt_pk_bf16_f32 v2, v11, v13
	v_cvt_pk_bf16_f32 v3, v4, v5
	v_cvt_pk_bf16_f32 v4, v12, v14
	v_cvt_pk_bf16_f32 v5, v8, v9
	global_store_dwordx4 v[6:7], v[2:5], off offset:256
